# v26 + one static s_setprio 1 for the trailing half-workgroup per GEMM phase (reset to 0 at the phase's unit-loop exit)
# speedup vs baseline: 1.0132x; 1.0005x over previous
; #define PG8_LAS __attribute__((address_space(3)))
; #define PG8_STAGE(bufoff, gbase, voff) do { _Pragma("unroll") for (int _i = 0; _i < 2; ++_i) \
;         __builtin_amdgcn_global_load_lds((const unsigned*)((const char*)(gbase) + (voff)[_i]), (PG8_LAS unsigned*)(lds + (bufoff) + ldsw + _i * 8192), 16, 0, 0); } while (0)
; #define PG8_WAIT_V(n) asm volatile("s_waitcnt vmcnt(" #n ")" ::: "memory")
; #define PG8_BAR __builtin_amdgcn_s_barrier()
; template <class Epi, class Sched, bool ALIGN_EPI = false, bool SP2 = false>
; __device__ __forceinline__ void gemm_phase(PG8_LAS unsigned char* lds, const Gemm g, const Sched& S, const Epi& E, int tid_in) {
;     ...
;         PG8_STAGE(PG8_SB(1, 0), cB + kstep, voffB); PG8_STAGE(PG8_SA(1, 0), cA + kstep, voffA); PG8_STAGE(PG8_SB(1, 1), cB + hstepB + kstep, voffB);
;         PG8_WAIT_V(6); PG8_BAR;
;     } else {
;         PG8_STAGE(PG8_SB(0, 0), cB, voffB); PG8_STAGE(PG8_SA(0, 0), cA, voffA); PG8_STAGE(PG8_SB(0, 1), cB + hstepB, voffB); PG8_STAGE(PG8_SA(0, 1), cA + hstep, voffA);
;         if (wr == 1) PG8_BAR;
;         PG8_WAIT_V(4); PG8_BAR;
;         PG8_STAGE(PG8_SB(1, 0), cB + kstep, voffB); PG8_STAGE(PG8_SA(1, 0), cA + kstep, voffA); PG8_STAGE(PG8_SB(1, 1), cB + hstepB + kstep, voffB);
;         PG8_WAIT_V(6); PG8_BAR;
;     }
;     for (;;) {
;         const bool has_next = S.next(ui + 1, nxt);
;         const char* nA = has_next ? (const char*)g.A + (size_t)nxt.pm * tstep : cA; const char* nB = has_next ? (const char*)g.Bt + (size_t)nxt.pn * tstepB : cB;
;         for (int t = 0; t < nt; t += 2) {
;     __device__ __forceinline__ void operator()(const f32x4 (&acc)[2][2][4][2], const Unit& u, int wr, int wc, int fr, int fq) const {
;         const int lane = fr + 16 * fq; PG8_LAS unsigned char* stg = lds + STG_OFF + (wr * 4 + wc) * STG_WAVE;
;         const PG8_LAS float* rtab = (const PG8_LAS float*)(lds + RSTD_OFF) + ((u.pm >> 3) & 3) * 256;
.LBB0_74:
	s_mov_b64 s[10:11], 0x80
	s_and_b32 s33, s7, 3
	s_add_i32 m0, s47, 0x18000
	v_lshl_add_u64 v[6:7], v[6:7], 0, s[10:11]
	s_lshl_b32 s60, s38, 6
	s_lshl_b32 s15, s38, 13
	s_lshl_b32 s39, s33, 12
	s_waitcnt vmcnt(2)
	s_barrier
	global_load_lds_dwordx4 v[6:7], off
	v_lshl_add_u64 v[4:5], v[4:5], 0, s[10:11]
	s_add_i32 m0, s47, 0x1a000
	s_add_i32 s61, s47, 0x8000
	s_add_i32 s62, s47, 0xa000
	global_load_lds_dwordx4 v[4:5], off
	v_lshl_add_u64 v[0:1], v[0:1], 0, s[10:11]
	s_mov_b32 m0, s61
	s_add_u32 s26, s50, 0x20080
	global_load_lds_dwordx4 v[0:1], off
	v_lshl_add_u64 v[0:1], v[2:3], 0, s[10:11]
	s_mov_b32 m0, s62
	s_addc_u32 s27, s51, 0
	global_load_lds_dwordx4 v[0:1], off
	s_add_i32 m0, s47, 0x1c000
	v_lshl_add_u64 v[0:1], s[26:27], 0, v[132:133]
	global_load_lds_dwordx4 v[0:1], off
	v_lshl_add_u64 v[0:1], s[26:27], 0, v[128:129]
	s_add_i32 m0, s47, 0x1e000
	v_and_b32_e32 v2, 48, v10
	global_load_lds_dwordx4 v[0:1], off
	v_and_b32_e32 v0, 15, v10
	v_lshlrev_b32_e32 v3, 2, v0
	v_lshl_or_b32 v1, v0, 6, v2
	v_and_b32_e32 v4, 32, v3
	s_cmpk_lt_u32 s14, 0x100
	s_sext_i32_i16 s69, s6
	v_bitop3_b32 v5, v1, s15, v4 bitop3:0xde
	s_cselect_b64 s[14:15], -1, 0
	s_lshl_b32 s6, s38, 2
	s_or_b32 s6, s6, s33
	s_mulk_i32 s6, 0x900
	s_lshl_b32 s26, s38, 8
	s_add_i32 s6, s6, 0
	s_add_i32 s26, s26, 0
	s_add_i32 s6, s6, 0x20000
	s_add_i32 s26, s26, 0x24800
	v_bitop3_b32 v146, v1, s39, v4 bitop3:0xde
	v_add_u32_e32 v147, s26, v3
	s_movk_i32 s26, 0x90
	v_mov_b32_e32 v1, s6
	v_mad_u32_u24 v3, v0, s26, v1
	v_and_b32_e32 v0, 0x70, v12
	v_add_u32_e32 v4, s6, v0
	s_lshl_b32 s6, s7, 7
	s_bfe_u32 s63, s7, 0x10001
	s_and_b32 s6, s6, 0x80
	s_add_u32 s6, s34, s6
	s_addc_u32 s7, s35, 0
	v_mov_b32_e32 v1, v133
	v_lshl_add_u64 v[136:137], s[6:7], 0, v[0:1]
	v_lshlrev_b32_e32 v0, 15, v14
	v_and_b32_e32 v0, 0xffff0000, v0
	v_lshl_add_u32 v0, v13, 12, v0
	v_and_b32_e32 v1, 1, v14
	v_lshl_or_b32 v0, v1, 6, v0
	v_lshl_add_u32 v138, v15, 1, v0
	v_lshlrev_b32_e32 v0, 15, v8
	v_and_b32_e32 v0, 0xffff0000, v0
	s_waitcnt vmcnt(6)
	v_bfe_u32 v148, v10, 3, 3
	v_lshl_add_u32 v0, v9, 12, v0
	v_and_b32_e32 v1, 1, v8
	v_mul_u32_u24_e32 v6, 0x90, v148
	v_lshl_or_b32 v0, v1, 6, v0
	s_add_i32 s67, 0, 0x10000
	s_add_i32 s68, 0, 0x14000
	v_or_b32_e32 v149, 8, v148
	s_or_b32 s64, s60, 16
	s_or_b32 s65, s60, 32
	s_or_b32 s66, s60, 48
	v_mov_b32_e32 v139, v133
	v_lshl_add_u32 v140, v11, 1, v0
	v_mov_b32_e32 v141, v133
	v_mov_b64_e32 v[142:143], 0xc00
	v_mov_b64_e32 v[144:145], 0xbff
	v_add_u32_e32 v150, s67, v146
	v_add_u32_e32 v151, s68, v146
	v_add_u32_e32 v152, 0, v5
	v_add_u32_e32 v153, v3, v2
	v_add_u32_e32 v154, v4, v6
	s_barrier
	s_waitcnt vmcnt(0)
	s_cmpk_gt_u32 s81, 0xff
	s_cbranch_scc0 .Lsp_0
	s_setprio 1
.Lsp_0:
	s_branch .LBB0_77
.LBB0_75:
	s_mov_b64 s[6:7], 0

; #define PG8_WAIT_V(n) asm volatile("s_waitcnt vmcnt(" #n ")" ::: "memory")
; #define PG8_BAR __builtin_amdgcn_s_barrier()
; template <class Epi, class Sched, bool ALIGN_EPI = false, bool SP2 = false>
; __device__ __forceinline__ void gemm_phase(PG8_LAS unsigned char* lds, const Gemm g, const Sched& S, const Epi& E, int tid_in) {
;     ...
;     PG8_WAIT_V(0);
;     if constexpr (!ALIGN_EPI) { if (wr == 0) PG8_BAR; }
;     PG8_BAR;
.LBB0_86:
	s_setprio 0
	s_waitcnt vmcnt(0)
	s_barrier

; #define PG8_LAS __attribute__((address_space(3)))
; #define PG8_STAGE(bufoff, gbase, voff) do { _Pragma("unroll") for (int _i = 0; _i < 2; ++_i) \
;         __builtin_amdgcn_global_load_lds((const unsigned*)((const char*)(gbase) + (voff)[_i]), (PG8_LAS unsigned*)(lds + (bufoff) + ldsw + _i * 8192), 16, 0, 0); } while (0)
; #define PG8_WAIT_V(n) asm volatile("s_waitcnt vmcnt(" #n ")" ::: "memory")
; #define PG8_BAR __builtin_amdgcn_s_barrier()
; template <class Epi, class Sched, bool ALIGN_EPI = false, bool SP2 = false>
; __device__ __forceinline__ void gemm_phase(PG8_LAS unsigned char* lds, const Gemm g, const Sched& S, const Epi& E, int tid_in) {
;     ...
;         PG8_STAGE(PG8_SB(1, 0), cB + kstep, voffB); PG8_STAGE(PG8_SA(1, 0), cA + kstep, voffA); PG8_STAGE(PG8_SB(1, 1), cB + hstepB + kstep, voffB);
;         PG8_WAIT_V(6); PG8_BAR;
;     } else {
;         PG8_STAGE(PG8_SB(0, 0), cB, voffB); PG8_STAGE(PG8_SA(0, 0), cA, voffA); PG8_STAGE(PG8_SB(0, 1), cB + hstepB, voffB); PG8_STAGE(PG8_SA(0, 1), cA + hstep, voffA);
;         if (wr == 1) PG8_BAR;
;         PG8_WAIT_V(4); PG8_BAR;
;         PG8_STAGE(PG8_SB(1, 0), cB + kstep, voffB); PG8_STAGE(PG8_SA(1, 0), cA + kstep, voffA); PG8_STAGE(PG8_SB(1, 1), cB + hstepB + kstep, voffB);
;         PG8_WAIT_V(6); PG8_BAR;
;     }
;     for (;;) {
;         const bool has_next = S.next(ui + 1, nxt);
;         const char* nA = has_next ? (const char*)g.A + (size_t)nxt.pm * tstep : cA; const char* nB = has_next ? (const char*)g.Bt + (size_t)nxt.pn * tstepB : cB;
;         for (int t = 0; t < nt; t += 2) {
;     __device__ __forceinline__ void operator()(const f32x4 (&acc)[2][2][4][2], const Unit& u, int wr, int wc, int fr, int fq) const {
;         const int lane = fr + 16 * fq, r = lane >> 2, p = lane & 3; PG8_LAS unsigned char* stg = lds + STG_OFF + (wr * 4 + wc) * STG_WAVE;
; #pragma unroll
;         for (int ai = 0; ai < 2; ++ai)
; #pragma unroll
;             for (int m = 0; m < 4; ++m) {
;                 const int row = u.pm * BM + ai * HALF + wr * 64 + m * 16 + r; float q = 0.f;
; #pragma unroll
;                 for (int bj = 0; bj < 2; ++bj) {
;                     const size_t off = (size_t)row * 2048 + u.pn * BM + wc * 64 + bj * 32 + 8 * p;
.LBB0_282:
	s_mov_b64 s[42:43], 0x80
	s_and_b32 s8, s8, 3
	s_add_i32 m0, s57, 0x18000
	v_lshl_add_u64 v[6:7], v[6:7], 0, s[42:43]
	s_lshl_b32 s11, s9, 13
	s_lshl_b32 s33, s8, 12
	s_waitcnt vmcnt(2)
	s_barrier
	global_load_lds_dwordx4 v[6:7], off
	v_lshl_add_u64 v[4:5], v[4:5], 0, s[42:43]
	s_add_i32 m0, s57, 0x1a000
	s_add_i32 s71, s57, 0x8000
	s_add_i32 s72, s57, 0xa000
	global_load_lds_dwordx4 v[4:5], off
	v_lshl_add_u64 v[0:1], v[0:1], 0, s[42:43]
	s_mov_b32 m0, s71
	s_add_u32 s26, s60, 0x20080
	global_load_lds_dwordx4 v[0:1], off
	v_lshl_add_u64 v[0:1], v[2:3], 0, s[42:43]
	s_mov_b32 m0, s72
	s_addc_u32 s27, s61, 0
	global_load_lds_dwordx4 v[0:1], off
	s_add_i32 m0, s57, 0x1c000
	v_lshl_add_u64 v[0:1], s[26:27], 0, v[130:131]
	global_load_lds_dwordx4 v[0:1], off
	v_lshl_add_u64 v[0:1], s[26:27], 0, v[134:135]
	s_add_i32 m0, s57, 0x1e000
	s_cmpk_lt_u32 s10, 0x100
	global_load_lds_dwordx4 v[0:1], off
	s_cselect_b64 s[44:45], -1, 0
	s_lshl_b32 s10, s9, 2
	v_and_b32_e32 v0, 15, v8
	v_and_b32_e32 v1, 48, v8
	v_lshlrev_b32_e32 v3, 2, v8
	s_or_b32 s10, s10, s8
	v_lshl_or_b32 v2, v0, 6, v1
	v_and_b32_e32 v3, 32, v3
	s_mulk_i32 s10, 0x900
	v_bitop3_b32 v4, v2, s11, v3 bitop3:0xde
	v_bitop3_b32 v137, v2, s33, v3 bitop3:0xde
	v_and_b32_e32 v3, 3, v8
	s_add_i32 s10, s10, 0
	v_bfe_u32 v2, v8, 2, 4
	v_lshlrev_b32_e32 v5, 3, v3
	s_add_i32 s10, s10, 0x20000
	v_lshl_or_b32 v150, s9, 6, v2
	v_lshl_or_b32 v136, s8, 6, v5
	v_lshlrev_b32_e32 v5, 5, v3
	v_cmp_eq_u32_e64 s[8:9], 0, v3
	s_movk_i32 s11, 0x90
	v_mov_b32_e32 v3, s10
	v_mad_u32_u24 v0, v0, s11, v3
	v_mad_u32_u24 v2, v2, s11, v3
	v_and_b32_e32 v3, 64, v252
	v_add_u32_e32 v3, 64, v3
	v_cmp_lt_i32_e32 vcc, v254, v3
	s_waitcnt vmcnt(6)
	s_add_i32 s73, 0, 0x10000
	s_add_i32 s74, 0, 0x14000
	v_cndmask_b32_e32 v6, v252, v254, vcc
	v_cmp_lt_i32_e32 vcc, v253, v3
	v_lshlrev_b32_e32 v151, 2, v6
	v_and_b32_e32 v6, 1, v9
	v_cndmask_b32_e32 v3, v252, v253, vcc
	v_lshlrev_b32_e32 v152, 2, v3
	v_lshlrev_b32_e32 v3, 15, v9
	v_and_b32_e32 v3, 0xffff0000, v3
	v_lshl_add_u32 v3, v10, 12, v3
	v_lshl_or_b32 v3, v6, 6, v3
	v_lshl_add_u32 v138, v11, 1, v3
	v_lshlrev_b32_e32 v3, 15, v12
	v_and_b32_e32 v3, 0xffff0000, v3
	v_lshl_add_u32 v3, v13, 12, v3
	v_and_b32_e32 v6, 1, v12
	v_lshl_or_b32 v3, v6, 6, v3
	v_mov_b32_e32 v139, v131
	v_lshl_add_u32 v140, v14, 1, v3
	v_mov_b32_e32 v141, v131
	v_mov_b64_e32 v[142:143], 0x400
	v_mov_b64_e32 v[144:145], 0x3ff
	v_add_u32_e32 v153, s73, v137
	v_add_u32_e32 v154, s74, v137
	v_add_u32_e32 v155, 0, v4
	v_add_u32_e32 v156, v0, v1
	v_add_u32_e32 v157, v2, v5
	s_barrier
	s_cmpk_gt_u32 s81, 0xff
	s_cbranch_scc0 .Lsp_1
	s_setprio 1
.Lsp_1:
	s_branch .LBB0_285
.LBB0_283:
	s_mov_b64 s[10:11], 0

; #define PG8_LAS __attribute__((address_space(3)))
; #define PG8_STAGE(bufoff, gbase, voff) do { _Pragma("unroll") for (int _i = 0; _i < 2; ++_i) \
;         __builtin_amdgcn_global_load_lds((const unsigned*)((const char*)(gbase) + (voff)[_i]), (PG8_LAS unsigned*)(lds + (bufoff) + ldsw + _i * 8192), 16, 0, 0); } while (0)
; #define PG8_WAIT_V(n) asm volatile("s_waitcnt vmcnt(" #n ")" ::: "memory")
; #define PG8_BAR __builtin_amdgcn_s_barrier()
; template <class Epi, class Sched, bool ALIGN_EPI = false, bool SP2 = false>
; __device__ __forceinline__ void gemm_phase(PG8_LAS unsigned char* lds, const Gemm g, const Sched& S, const Epi& E, int tid_in) {
;     ...
;         PG8_STAGE(PG8_SB(1, 0), cB + kstep, voffB); PG8_STAGE(PG8_SA(1, 0), cA + kstep, voffA); PG8_STAGE(PG8_SB(1, 1), cB + hstepB + kstep, voffB);
;         PG8_WAIT_V(6); PG8_BAR;
;     } else {
;         PG8_STAGE(PG8_SB(0, 0), cB, voffB); PG8_STAGE(PG8_SA(0, 0), cA, voffA); PG8_STAGE(PG8_SB(0, 1), cB + hstepB, voffB); PG8_STAGE(PG8_SA(0, 1), cA + hstep, voffA);
;         if (wr == 1) PG8_BAR;
;         PG8_WAIT_V(4); PG8_BAR;
;         PG8_STAGE(PG8_SB(1, 0), cB + kstep, voffB); PG8_STAGE(PG8_SA(1, 0), cA + kstep, voffA); PG8_STAGE(PG8_SB(1, 1), cB + hstepB + kstep, voffB);
;         PG8_WAIT_V(6); PG8_BAR;
;     }
;     for (;;) {
;         const bool has_next = S.next(ui + 1, nxt);
;         const char* nA = has_next ? (const char*)g.A + (size_t)nxt.pm * tstep : cA; const char* nB = has_next ? (const char*)g.Bt + (size_t)nxt.pn * tstepB : cB;
;         for (int t = 0; t < nt; t += 2) {
;     __device__ __forceinline__ void operator()(const f32x4 (&acc)[2][2][4][2], const Unit& u, int wr, int wc, int fr, int fq) const {
;         const int lane = fr + 16 * fq; PG8_LAS unsigned char* stg = lds + STG_OFF + (wr * 4 + wc) * STG_WAVE;
;         const PG8_LAS float* rtab = (const PG8_LAS float*)(lds + RSTD_OFF) + ((u.pm >> 3) & 3) * 256;
; #pragma unroll
;         for (int ai = 0; ai < 2; ++ai)
; #pragma unroll
;             for (int m = 0; m < 4; ++m) {
;                 const int rowg0 = u.pm * BM + ai * HALF + wr * 64 + m * 16; const float rs = rtab[ai * HALF + wr * 64 + m * 16 + fr];
.LBB0_384:
	s_mov_b64 s[12:13], 0x80
	s_and_b32 s9, s9, 3
	s_add_i32 m0, s51, 0x18000
	v_lshl_add_u64 v[6:7], v[6:7], 0, s[12:13]
	s_lshl_b32 s65, s33, 6
	s_lshl_b32 s15, s33, 13
	s_lshl_b32 s42, s9, 12
	s_waitcnt vmcnt(2)
	s_barrier
	global_load_lds_dwordx4 v[6:7], off
	v_lshl_add_u64 v[4:5], v[4:5], 0, s[12:13]
	s_add_i32 m0, s51, 0x1a000
	s_add_i32 s66, s51, 0x8000
	s_add_i32 s67, s51, 0xa000
	global_load_lds_dwordx4 v[4:5], off
	v_lshl_add_u64 v[0:1], v[0:1], 0, s[12:13]
	s_mov_b32 m0, s66
	s_add_u32 s26, s54, 0x20080
	global_load_lds_dwordx4 v[0:1], off
	v_lshl_add_u64 v[0:1], v[2:3], 0, s[12:13]
	s_mov_b32 m0, s67
	s_addc_u32 s27, s55, 0
	global_load_lds_dwordx4 v[0:1], off
	s_add_i32 m0, s51, 0x1c000
	v_lshl_add_u64 v[0:1], s[26:27], 0, v[130:131]
	global_load_lds_dwordx4 v[0:1], off
	v_lshl_add_u64 v[0:1], s[26:27], 0, v[134:135]
	s_add_i32 m0, s51, 0x1e000
	v_and_b32_e32 v2, 15, v8
	global_load_lds_dwordx4 v[0:1], off
	v_and_b32_e32 v3, 48, v8
	v_lshlrev_b32_e32 v1, 2, v2
	v_lshl_or_b32 v0, v2, 6, v3
	v_and_b32_e32 v4, 32, v1
	s_cmpk_lt_u32 s14, 0x100
	s_sext_i32_i16 s71, s8
	v_bitop3_b32 v5, v0, s15, v4 bitop3:0xde
	s_cselect_b64 s[14:15], -1, 0
	s_lshl_b32 s8, s33, 2
	s_or_b32 s8, s8, s9
	s_mul_i32 s26, s8, 0x900
	s_lshl_b32 s8, s33, 8
	s_add_i32 s8, s8, 0
	s_add_i32 s8, s8, 0x24800
	v_add_u32_e32 v149, s8, v1
	s_lshl_b32 s8, s9, 7
	s_add_u32 s8, s34, s8
	v_bitop3_b32 v146, v0, s42, v4 bitop3:0xde
	v_and_b32_e32 v0, 0x70, v12
	s_addc_u32 s9, s35, 0
	v_mov_b32_e32 v1, v131
	v_lshl_add_u64 v[136:137], s[8:9], 0, v[0:1]
	s_add_i32 s8, s26, 0
	s_add_i32 s8, s8, 0x20000
	s_movk_i32 s27, 0x90
	v_mov_b32_e32 v1, s8
	v_mad_u32_u24 v1, v2, s27, v1
	v_lshlrev_b32_e32 v2, 15, v9
	v_and_b32_e32 v2, 0xffff0000, v2
	v_lshl_add_u32 v2, v10, 12, v2
	v_and_b32_e32 v6, 1, v9
	v_lshl_or_b32 v2, v6, 6, v2
	v_lshl_add_u32 v138, v11, 1, v2
	v_lshlrev_b32_e32 v2, 15, v13
	v_and_b32_e32 v2, 0xffff0000, v2
	s_waitcnt vmcnt(6)
	v_bfe_u32 v147, v8, 3, 3
	v_lshl_add_u32 v2, v14, 12, v2
	v_and_b32_e32 v6, 1, v13
	v_mul_u32_u24_e32 v4, 0x90, v147
	v_add_u32_e32 v0, s8, v0
	v_lshl_or_b32 v2, v6, 6, v2
	s_add_i32 s68, 0, 0x10000
	s_add_i32 s69, 0, 0x14000
	v_or_b32_e32 v148, 8, v147
	v_mov_b32_e32 v139, v131
	v_lshl_add_u32 v140, v15, 1, v2
	v_mov_b32_e32 v141, v131
	v_mov_b64_e32 v[142:143], 0x1000
	v_mov_b64_e32 v[144:145], 0xfff
	v_add_u32_e32 v150, s68, v146
	v_add_u32_e32 v151, s69, v146
	v_add_u32_e32 v152, 0, v5
	v_add_u32_e32 v153, v1, v3
	v_add_u32_e32 v154, v0, v4
	s_movk_i32 s70, 0x4080
	s_barrier
	s_waitcnt vmcnt(0)
	s_cmpk_gt_u32 s81, 0xff
	s_cbranch_scc0 .Lsp_2
	s_setprio 1
.Lsp_2:
	s_branch .LBB0_387
.LBB0_385:
	s_mov_b64 s[8:9], 0

; #define PG8_LAS __attribute__((address_space(3)))
; #define PG8_STAGE(bufoff, gbase, voff) do { _Pragma("unroll") for (int _i = 0; _i < 2; ++_i) \
;         __builtin_amdgcn_global_load_lds((const unsigned*)((const char*)(gbase) + (voff)[_i]), (PG8_LAS unsigned*)(lds + (bufoff) + ldsw + _i * 8192), 16, 0, 0); } while (0)
; #define PG8_WAIT_V(n) asm volatile("s_waitcnt vmcnt(" #n ")" ::: "memory")
; #define PG8_BAR __builtin_amdgcn_s_barrier()
; template <class Epi, class Sched, bool ALIGN_EPI = false, bool SP2 = false>
; __device__ __forceinline__ void gemm_phase(PG8_LAS unsigned char* lds, const Gemm g, const Sched& S, const Epi& E, int tid_in) {
;     ...
;         PG8_STAGE(PG8_SB(1, 0), cB + kstep, voffB); PG8_STAGE(PG8_SA(1, 0), cA + kstep, voffA); PG8_STAGE(PG8_SB(1, 1), cB + hstepB + kstep, voffB);
;         PG8_WAIT_V(6); PG8_BAR;
;     } else {
;         PG8_STAGE(PG8_SB(0, 0), cB, voffB); PG8_STAGE(PG8_SA(0, 0), cA, voffA); PG8_STAGE(PG8_SB(0, 1), cB + hstepB, voffB); PG8_STAGE(PG8_SA(0, 1), cA + hstep, voffA);
;         if (wr == 1) PG8_BAR;
;         PG8_WAIT_V(4); PG8_BAR;
;         PG8_STAGE(PG8_SB(1, 0), cB + kstep, voffB); PG8_STAGE(PG8_SA(1, 0), cA + kstep, voffA); PG8_STAGE(PG8_SB(1, 1), cB + hstepB + kstep, voffB);
;         PG8_WAIT_V(6); PG8_BAR;
;     }
;     for (;;) {
;         const bool has_next = S.next(ui + 1, nxt);
;         const char* nA = has_next ? (const char*)g.A + (size_t)nxt.pm * tstep : cA; const char* nB = has_next ? (const char*)g.Bt + (size_t)nxt.pn * tstepB : cB;
;         for (int t = 0; t < nt; t += 2) {
;     __device__ __forceinline__ void operator()(const f32x4 (&acc)[2][2][4][2], const Unit& u, int wr, int wc, int fr, int fq) const {
;         const int lane = fr + 16 * fq, r = lane >> 2, p = lane & 3; PG8_LAS unsigned char* stg = lds + STG_OFF + (wr * 4 + wc) * STG_WAVE;
; #pragma unroll
;         for (int ai = 0; ai < 2; ++ai)
; #pragma unroll
;             for (int m = 0; m < 4; ++m) {
;                 const int row = u.pm * BM + ai * HALF + wr * 64 + m * 16 + r; float q = 0.f;
; #pragma unroll
;                 for (int bj = 0; bj < 2; ++bj) {
;                     const size_t off = (size_t)row * 2048 + u.pn * BM + wc * 64 + bj * 32 + 8 * p;
.LBB0_462:
	s_mov_b64 s[42:43], 0x80
	s_and_b32 s8, s8, 3
	s_add_i32 m0, s55, 0x18000
	v_lshl_add_u64 v[6:7], v[6:7], 0, s[42:43]
	s_lshl_b32 s26, s9, 13
	s_lshl_b32 s27, s8, 12
	s_waitcnt vmcnt(2)
	s_barrier
	global_load_lds_dwordx4 v[6:7], off
	v_lshl_add_u64 v[4:5], v[4:5], 0, s[42:43]
	s_add_i32 m0, s55, 0x1a000
	s_add_i32 s69, s55, 0x8000
	s_add_i32 s70, s55, 0xa000
	global_load_lds_dwordx4 v[4:5], off
	v_lshl_add_u64 v[0:1], v[0:1], 0, s[42:43]
	s_mov_b32 m0, s69
	s_add_u32 s12, s58, 0x80080
	global_load_lds_dwordx4 v[0:1], off
	v_lshl_add_u64 v[0:1], v[2:3], 0, s[42:43]
	s_mov_b32 m0, s70
	s_addc_u32 s13, s59, 0
	global_load_lds_dwordx4 v[0:1], off
	s_add_i32 m0, s55, 0x1c000
	v_lshl_add_u64 v[0:1], s[12:13], 0, v[130:131]
	global_load_lds_dwordx4 v[0:1], off
	v_lshl_add_u64 v[0:1], s[12:13], 0, v[134:135]
	s_add_i32 m0, s55, 0x1e000
	s_cmpk_lt_u32 s10, 0x100
	global_load_lds_dwordx4 v[0:1], off
	s_cselect_b64 s[46:47], -1, 0
	s_lshl_b32 s10, s9, 2
	v_and_b32_e32 v2, 48, v8
	v_and_b32_e32 v0, 15, v8
	v_lshlrev_b32_e32 v3, 2, v8
	s_or_b32 s10, s10, s8
	v_lshl_or_b32 v1, v0, 6, v2
	v_and_b32_e32 v3, 32, v3
	s_mulk_i32 s10, 0x900
	v_bitop3_b32 v4, v1, s26, v3 bitop3:0xde
	v_bitop3_b32 v137, v1, s27, v3 bitop3:0xde
	v_and_b32_e32 v3, 3, v8
	s_add_i32 s10, s10, 0
	v_bfe_u32 v1, v8, 2, 4
	v_lshlrev_b32_e32 v5, 3, v3
	s_add_i32 s10, s10, 0x20000
	v_lshl_or_b32 v150, s9, 6, v1
	v_lshl_or_b32 v136, s8, 6, v5
	v_lshlrev_b32_e32 v5, 5, v3
	v_cmp_eq_u32_e64 s[8:9], 0, v3
	s_movk_i32 s12, 0x90
	v_mov_b32_e32 v3, s10
	v_mad_u32_u24 v6, v0, s12, v3
	v_and_b32_e32 v0, 64, v252
	v_add_u32_e32 v0, 64, v0
	v_cmp_lt_i32_e32 vcc, v254, v0
	v_mad_u32_u24 v3, v1, s12, v3
	s_mov_b32 s10, 0x20400
	v_cndmask_b32_e32 v1, v252, v254, vcc
	v_cmp_lt_i32_e32 vcc, v253, v0
	v_lshlrev_b32_e32 v151, 2, v1
	v_lshrrev_b32_e32 v1, 1, v9
	v_cndmask_b32_e32 v0, v252, v253, vcc
	v_lshlrev_b32_e32 v152, 2, v0
	v_mul_lo_u32 v0, v11, s11
	v_mad_u64_u32 v[0:1], s[12:13], v1, s10, v[0:1]
	v_or_b32_e32 v0, v0, v10
	v_add_lshl_u32 v0, v0, v12, 1
	v_mov_b32_e32 v1, v131
	s_mov_b64 s[12:13], 0x204080
	v_lshl_add_u64 v[138:139], v[0:1], 0, s[12:13]
	v_lshrrev_b32_e32 v1, 1, v13
	v_mul_lo_u32 v0, v14, s11
	v_mad_u64_u32 v[0:1], s[10:11], v1, s10, v[0:1]
	s_waitcnt vmcnt(6)
	v_or_b32_e32 v0, v0, v15
	v_add_lshl_u32 v0, v0, v16, 1
	v_mov_b32_e32 v1, v131
	s_add_i32 s71, 0, 0x10000
	s_add_i32 s72, 0, 0x14000
	v_lshl_add_u64 v[140:141], v[0:1], 0, s[12:13]
	v_mov_b64_e32 v[142:143], 0x400
	v_mov_b64_e32 v[144:145], 0x3ff
	v_add_u32_e32 v153, s71, v137
	v_add_u32_e32 v154, s72, v137
	v_add_u32_e32 v155, 0, v4
	v_add_u32_e32 v156, v6, v2
	v_add_u32_e32 v157, v3, v5
	s_barrier
	s_cmpk_gt_u32 s81, 0xff
	s_cbranch_scc0 .Lsp_3
	s_setprio 1
.Lsp_3:
	s_branch .LBB0_465
.LBB0_463:
	s_mov_b64 s[10:11], 0

; #define PG8_LAS __attribute__((address_space(3)))
; #define PG8_STAGE(bufoff, gbase, voff) do { _Pragma("unroll") for (int _i = 0; _i < 2; ++_i) \
;         __builtin_amdgcn_global_load_lds((const unsigned*)((const char*)(gbase) + (voff)[_i]), (PG8_LAS unsigned*)(lds + (bufoff) + ldsw + _i * 8192), 16, 0, 0); } while (0)
; template <class Epi, class Sched, bool ALIGN_EPI = false, bool SP2 = false>
; __device__ __forceinline__ void gemm_phase(PG8_LAS unsigned char* lds, const Gemm g, const Sched& S, const Epi& E, int tid_in) {
;     ...
;         PG8_STAGE(PG8_SB(1, 0), cB + kstep, voffB); PG8_STAGE(PG8_SA(1, 0), cA + kstep, voffA); PG8_STAGE(PG8_SB(1, 1), cB + hstepB + kstep, voffB);
;         PG8_WAIT_V(6); PG8_BAR;
;     } else {
;         PG8_STAGE(PG8_SB(0, 0), cB, voffB); PG8_STAGE(PG8_SA(0, 0), cA, voffA); PG8_STAGE(PG8_SB(0, 1), cB + hstepB, voffB); PG8_STAGE(PG8_SA(0, 1), cA + hstep, voffA);
;         if (wr == 1) PG8_BAR;
;         PG8_WAIT_V(4); PG8_BAR;
;         PG8_STAGE(PG8_SB(1, 0), cB + kstep, voffB); PG8_STAGE(PG8_SA(1, 0), cA + kstep, voffA); PG8_STAGE(PG8_SB(1, 1), cB + hstepB + kstep, voffB);
;         PG8_WAIT_V(6); PG8_BAR;
;     }
;     for (;;) {
;         const bool has_next = S.next(ui + 1, nxt);
;         const char* nA = has_next ? (const char*)g.A + (size_t)nxt.pm * tstep : cA; const char* nB = has_next ? (const char*)g.Bt + (size_t)nxt.pn * tstepB : cB;
;         for (int t = 0; t < nt; t += 2) {
;     __device__ __forceinline__ void operator()(const f32x4 (&acc)[2][2][4][2], const Unit& u, int wr, int wc, int fr, int fq) const {
;         const int lane = fr + 16 * fq; PG8_LAS unsigned char* stg = lds + STG_OFF + (wr * 4 + wc) * STG_WAVE;
;         const bool rot = ((wc & 1) == 0) && (((u.pn >> 2) % 3) != 2);
;         const PG8_LAS float* rtab = (const PG8_LAS float*)(lds + RSTD_OFF) + ((u.pm >> 3) & 3) * 256;
; #pragma unroll
;         for (int ai = 0; ai < 2; ++ai)
; #pragma unroll
;             for (int m = 0; m < 4; ++m) {
;                 const int rowg0 = u.pm * BM + ai * HALF + wr * 64 + m * 16, row = rowg0 + fr; const float rs = rtab[ai * HALF + wr * 64 + m * 16 + fr];
;                 f32x4 c4 = {1.f, 1.f, 1.f, 1.f}, s4 = {0.f, 0.f, 0.f, 0.f};
;                 if (rot) { const int t = row & 16383; c4 = *(const f32x4*)(cst + t * 16 + 4 * fq); s4 = *(const f32x4*)(snt + t * 16 + 4 * fq); }
.LBB0_591:
	s_mov_b64 s[44:45], 0x80
	s_and_b32 s11, s8, 3
	s_add_i32 m0, s59, 0x18000
	v_lshl_add_u64 v[6:7], v[6:7], 0, s[44:45]
	s_lshl_b32 s73, s9, 6
	s_lshl_b32 s33, s9, 13
	s_lshl_b32 s46, s11, 12
	s_waitcnt vmcnt(2)
	s_barrier
	global_load_lds_dwordx4 v[6:7], off
	v_lshl_add_u64 v[4:5], v[4:5], 0, s[44:45]
	s_add_i32 m0, s59, 0x1a000
	s_add_i32 s74, s59, 0x8000
	s_add_i32 s75, s59, 0xa000
	global_load_lds_dwordx4 v[4:5], off
	v_lshl_add_u64 v[0:1], v[0:1], 0, s[44:45]
	s_mov_b32 m0, s74
	s_add_u32 s26, s62, 0x20080
	global_load_lds_dwordx4 v[0:1], off
	v_lshl_add_u64 v[0:1], v[2:3], 0, s[44:45]
	s_mov_b32 m0, s75
	s_addc_u32 s27, s63, 0
	global_load_lds_dwordx4 v[0:1], off
	s_add_i32 m0, s59, 0x1c000
	v_lshl_add_u64 v[0:1], s[26:27], 0, v[144:145]
	global_load_lds_dwordx4 v[0:1], off
	v_lshl_add_u64 v[0:1], s[26:27], 0, v[148:149]
	s_add_i32 m0, s59, 0x1e000
	v_and_b32_e32 v166, 15, v8
	global_load_lds_dwordx4 v[0:1], off
	v_bfe_u32 v0, v8, 4, 2
	v_lshlrev_b32_e32 v150, 4, v0
	v_lshlrev_b32_e32 v1, 2, v166
	v_lshlrev_b32_e32 v4, 3, v0
	v_lshl_or_b32 v0, v166, 6, v150
	v_and_b32_e32 v2, 32, v1
	s_cmpk_lt_u32 s48, 0x100
	v_bitop3_b32 v167, v0, s46, v2 bitop3:0xde
	s_cselect_b64 s[46:47], -1, 0
	s_lshl_b32 s26, s9, 2
	s_or_b32 s11, s26, s11
	v_bitop3_b32 v5, v0, s33, v2 bitop3:0xde
	s_bitcmp0_b32 s48, 6
	v_lshl_add_u64 v[2:3], s[18:19], 0, v[150:151]
	s_mov_b64 s[26:27], 0x300000
	s_cselect_b64 s[48:49], -1, 0
	s_lshl_b32 s9, s9, 8
	v_lshl_add_u64 v[152:153], v[2:3], 0, s[26:27]
	s_mov_b64 s[26:27], 0x200000
	s_bfe_u32 s76, s8, 0x10001
	s_add_i32 s9, s9, 0
	v_lshl_add_u64 v[154:155], v[2:3], 0, s[26:27]
	s_lshl_b32 s8, s8, 7
	v_lshlrev_b32_e32 v2, 15, v9
	s_add_i32 s9, s9, 0x24800
	s_and_b32 s8, s8, 0x80
	v_and_b32_e32 v2, 0xffff0000, v2
	s_add_u32 s8, s34, s8
	v_lshl_add_u32 v2, v10, 12, v2
	v_and_b32_e32 v3, 1, v9
	s_mulk_i32 s11, 0x900
	v_and_b32_e32 v0, 0x70, v13
	v_add_u32_e32 v170, s9, v1
	s_addc_u32 s9, s35, 0
	v_mov_b32_e32 v1, v151
	v_lshl_or_b32 v2, v3, 6, v2
	v_lshl_add_u64 v[156:157], s[8:9], 0, v[0:1]
	s_add_i32 s8, s11, 0
	v_lshl_add_u32 v158, v11, 1, v2
	v_lshlrev_b32_e32 v2, 15, v12
	s_add_i32 s8, s8, 0x20000
	v_and_b32_e32 v2, 0xffff0000, v2
	s_waitcnt vmcnt(6)
	v_bfe_u32 v168, v8, 3, 3
	s_movk_i32 s33, 0x90
	v_mov_b32_e32 v1, s8
	v_lshl_add_u32 v2, v14, 12, v2
	v_and_b32_e32 v3, 1, v12
	v_mul_u32_u24_e32 v6, 0x90, v168
	v_mad_u32_u24 v1, v166, s33, v1
	v_add_u32_e32 v0, s8, v0
	v_lshl_or_b32 v2, v3, 6, v2
	s_add_i32 s78, 0, 0x10000
	s_add_i32 s79, 0, 0x14000
	v_or_b32_e32 v169, 8, v168
	v_mov_b32_e32 v159, v151
	v_lshl_add_u32 v160, v15, 1, v2
	v_mov_b32_e32 v161, v151
	v_mov_b64_e32 v[162:163], 0x1200
	v_mov_b64_e32 v[164:165], 0x11ff
	s_movk_i32 s77, 0x241
	v_add_u32_e32 v171, s78, v167
	v_add_u32_e32 v172, s79, v167
	v_add_u32_e32 v173, 0, v5
	s_movk_i32 s84, 0x3fff
	v_add_u32_e32 v174, v1, v4
	v_add_u32_e32 v175, v0, v6
	v_mov_b32_e32 v176, 0x3fc7
	v_mov_b32_e32 v177, 0x3fcf
	v_mov_b32_e32 v178, 0x3fd7
	v_mov_b32_e32 v179, 0x3fdf
	v_mov_b32_e32 v180, 0x3fe7
	v_mov_b32_e32 v181, 0x3fef
	v_mov_b32_e32 v182, 0x3ff7
	v_mov_b32_e32 v183, 0x3fff
	s_barrier
	s_cmpk_gt_u32 s81, 0xff
	s_cbranch_scc0 .Lsp_4
	s_setprio 1
.Lsp_4:
	s_branch .LBB0_594
.LBB0_592:
	s_mov_b64 s[8:9], 0

; #define PG8_LAS __attribute__((address_space(3)))
; #define PG8_STAGE(bufoff, gbase, voff) do { _Pragma("unroll") for (int _i = 0; _i < 2; ++_i) \
;         __builtin_amdgcn_global_load_lds((const unsigned*)((const char*)(gbase) + (voff)[_i]), (PG8_LAS unsigned*)(lds + (bufoff) + ldsw + _i * 8192), 16, 0, 0); } while (0)
; #define PG8_WAIT_V(n) asm volatile("s_waitcnt vmcnt(" #n ")" ::: "memory")
; #define PG8_BAR __builtin_amdgcn_s_barrier()
; template <class Epi, class Sched, bool ALIGN_EPI = false, bool SP2 = false>
; __device__ __forceinline__ void gemm_phase(PG8_LAS unsigned char* lds, const Gemm g, const Sched& S, const Epi& E, int tid_in) {
;     ...
;         PG8_WAIT_V(2); PG8_BAR;
;         PG8_STAGE(PG8_SB(1, 0), cB + kstep, voffB); PG8_STAGE(PG8_SA(1, 0), cA + kstep, voffA); PG8_STAGE(PG8_SB(1, 1), cB + hstepB + kstep, voffB);
;         PG8_WAIT_V(6); PG8_BAR;
;     __device__ __forceinline__ void operator()(const f32x4 (&acc)[2][2][4][2], const Unit& u, int wr, int wc, int fr, int fq) const {
;         const int lane = fr + 16 * fq, r = lane >> 2, p = lane & 3; PG8_LAS unsigned char* stg = lds + STG_OFF + (wr * 4 + wc) * STG_WAVE;
; #pragma unroll
;         for (int ai = 0; ai < 2; ++ai)
; #pragma unroll
;             for (int m = 0; m < 4; ++m) {
;                 const int row = u.pm * BM + ai * HALF + wr * 64 + m * 16 + r; float q = 0.f;
; #pragma unroll
;                 for (int bj = 0; bj < 2; ++bj) {
;                     const size_t off = (size_t)row * 2048 + u.pn * BM + wc * 64 + bj * 32 + 8 * p;
.LBB0_757:
	s_mov_b64 s[46:47], 0x80
	s_and_b32 s8, s8, 3
	s_add_i32 m0, s61, 0x18000
	v_lshl_add_u64 v[6:7], v[6:7], 0, s[46:47]
	s_lshl_b32 s11, s9, 13
	s_lshl_b32 s33, s8, 12
	s_waitcnt vmcnt(2)
	s_barrier
	global_load_lds_dwordx4 v[6:7], off
	v_lshl_add_u64 v[4:5], v[4:5], 0, s[46:47]
	s_add_i32 m0, s61, 0x1a000
	s_add_i32 s73, s61, 0x8000
	s_add_i32 s74, s61, 0xa000
	global_load_lds_dwordx4 v[4:5], off
	v_lshl_add_u64 v[0:1], v[0:1], 0, s[46:47]
	s_mov_b32 m0, s73
	s_add_u32 s26, s64, 0x10080
	global_load_lds_dwordx4 v[0:1], off
	v_lshl_add_u64 v[0:1], v[2:3], 0, s[46:47]
	s_mov_b32 m0, s74
	s_addc_u32 s27, s65, 0
	global_load_lds_dwordx4 v[0:1], off
	s_add_i32 m0, s61, 0x1c000
	v_lshl_add_u64 v[0:1], s[26:27], 0, v[130:131]
	global_load_lds_dwordx4 v[0:1], off
	v_lshl_add_u64 v[0:1], s[26:27], 0, v[134:135]
	s_add_i32 m0, s61, 0x1e000
	s_cmpk_lt_u32 s10, 0x100
	global_load_lds_dwordx4 v[0:1], off
	s_cselect_b64 s[48:49], -1, 0
	s_lshl_b32 s10, s9, 2
	v_and_b32_e32 v0, 48, v8
	v_and_b32_e32 v1, 15, v8
	v_lshlrev_b32_e32 v3, 2, v8
	s_or_b32 s10, s10, s8
	v_lshl_or_b32 v2, v1, 6, v0
	v_and_b32_e32 v3, 32, v3
	s_mulk_i32 s10, 0x900
	v_bitop3_b32 v4, v2, s11, v3 bitop3:0xde
	v_bitop3_b32 v137, v2, s33, v3 bitop3:0xde
	v_and_b32_e32 v3, 3, v8
	s_add_i32 s10, s10, 0
	v_bfe_u32 v2, v8, 2, 4
	v_lshlrev_b32_e32 v5, 3, v3
	s_add_i32 s10, s10, 0x20000
	v_lshl_or_b32 v150, s9, 6, v2
	v_lshl_or_b32 v136, s8, 6, v5
	v_lshlrev_b32_e32 v5, 5, v3
	v_cmp_eq_u32_e64 s[8:9], 0, v3
	s_movk_i32 s11, 0x90
	v_mov_b32_e32 v3, s10
	v_mad_u32_u24 v1, v1, s11, v3
	v_mad_u32_u24 v2, v2, s11, v3
	v_and_b32_e32 v3, 64, v252
	v_add_u32_e32 v3, 64, v3
	v_cmp_lt_i32_e32 vcc, v254, v3
	s_waitcnt vmcnt(6)
	s_add_i32 s75, 0, 0x10000
	s_add_i32 s76, 0, 0x14000
	v_cndmask_b32_e32 v6, v252, v254, vcc
	v_cmp_lt_i32_e32 vcc, v253, v3
	v_lshlrev_b32_e32 v151, 2, v6
	v_and_b32_e32 v6, 1, v9
	v_cndmask_b32_e32 v3, v252, v253, vcc
	v_lshlrev_b32_e32 v152, 2, v3
	v_lshlrev_b32_e32 v3, 14, v9
	v_and_b32_e32 v3, 0xffff8000, v3
	v_lshl_add_u32 v3, v10, 11, v3
	v_lshl_or_b32 v3, v6, 6, v3
	v_lshl_add_u32 v138, v11, 1, v3
	v_lshlrev_b32_e32 v3, 14, v12
	v_and_b32_e32 v3, 0xffff8000, v3
	v_lshl_add_u32 v3, v13, 11, v3
	v_and_b32_e32 v6, 1, v12
	v_lshl_or_b32 v3, v6, 6, v3
	v_mov_b32_e32 v139, v131
	v_lshl_add_u32 v140, v14, 1, v3
	v_mov_b32_e32 v141, v131
	v_mov_b64_e32 v[142:143], 0x400
	v_mov_b64_e32 v[144:145], 0x3ff
	v_add_u32_e32 v153, s75, v137
	v_add_u32_e32 v154, s76, v137
	v_add_u32_e32 v155, 0, v4
	v_add_u32_e32 v156, v1, v0
	v_add_u32_e32 v157, v2, v5
	s_barrier
	s_cmpk_gt_u32 s81, 0xff
	s_cbranch_scc0 .Lsp_5
	s_setprio 1
.Lsp_5:
	s_branch .LBB0_760
.LBB0_758:
	s_mov_b64 s[10:11], 0

; #define PG8_LAS __attribute__((address_space(3)))
; __device__ __forceinline__ unsigned cvt_pk_bf16(float lo, float hi) { unsigned r; asm volatile("v_cvt_pk_bf16_f32 %0, %1, %2" : "=v"(r) : "v"(lo), "v"(hi)); return r; }
; #define PG8_STAGE(bufoff, gbase, voff) do { _Pragma("unroll") for (int _i = 0; _i < 2; ++_i) \
;         __builtin_amdgcn_global_load_lds((const unsigned*)((const char*)(gbase) + (voff)[_i]), (PG8_LAS unsigned*)(lds + (bufoff) + ldsw + _i * 8192), 16, 0, 0); } while (0)
; #define PG8_WAIT_V(n) asm volatile("s_waitcnt vmcnt(" #n ")" ::: "memory")
; #define PG8_BAR __builtin_amdgcn_s_barrier()
; template <class Epi, class Sched, bool ALIGN_EPI = false, bool SP2 = false>
; __device__ __forceinline__ void gemm_phase(PG8_LAS unsigned char* lds, const Gemm g, const Sched& S, const Epi& E, int tid_in) {
;     ...
;         PG8_WAIT_V(2); PG8_BAR;
;         PG8_STAGE(PG8_SB(1, 0), cB + kstep, voffB); PG8_STAGE(PG8_SA(1, 0), cA + kstep, voffA); PG8_STAGE(PG8_SB(1, 1), cB + hstepB + kstep, voffB);
;         PG8_WAIT_V(6); PG8_BAR;
;     __device__ __forceinline__ void operator()(const f32x4 (&acc)[2][2][4][2], const Unit& u, int wr, int wc, int fr, int fq) const {
;         const int lane = fr + 16 * fq; PG8_LAS unsigned char* stg = lds + STG_OFF + (wr * 4 + wc) * STG_WAVE;
;         const PG8_LAS float* rtab = (const PG8_LAS float*)(lds + RSTD_OFF) + ((u.pm >> 3) & 3) * 256;
; #pragma unroll
;         for (int ai = 0; ai < 2; ++ai)
; #pragma unroll
;             for (int m = 0; m < 4; ++m) {
;                 const int rowg0 = u.pm * BM + ai * HALF + wr * 64 + m * 16; const float rs = rtab[ai * HALF + wr * 64 + m * 16 + fr];
; #pragma unroll
;                 for (int bj = 0; bj < 2; ++bj) {
;                     f32x4 v0 = acc[ai][bj][m][0] * rs, v1 = acc[ai][bj][m][1] * rs;
;                     if (ACT == 1) { const f32x4 z = {0.f, 0.f, 0.f, 0.f}; v0 = __builtin_elementwise_max(v0, z); v1 = __builtin_elementwise_max(v1, z); v0 = v0 * v0; v1 = v1 * v1; }
;                     u32x4 w; w.x = cvt_pk_bf16(v0[0], v0[1]); w.y = cvt_pk_bf16(v0[2], v0[3]); w.z = cvt_pk_bf16(v1[0], v1[1]); w.w = cvt_pk_bf16(v1[2], v1[3]);
;                     *(PG8_LAS u32x4*)(stg + fr * STG_ROW + bj * 64 + fq * 16) = w; }
.LBB0_859:
	s_mov_b64 s[12:13], 0x80
	s_and_b32 s9, s9, 3
	s_add_i32 m0, s49, 0x18000
	v_lshl_add_u64 v[6:7], v[6:7], 0, s[12:13]
	s_lshl_b32 s61, s33, 6
	s_lshl_b32 s37, s33, 13
	s_lshl_b32 s38, s9, 12
	s_waitcnt vmcnt(2)
	s_barrier
	global_load_lds_dwordx4 v[6:7], off
	v_lshl_add_u64 v[4:5], v[4:5], 0, s[12:13]
	s_add_i32 m0, s49, 0x1a000
	s_add_i32 s62, s49, 0x8000
	s_add_i32 s63, s49, 0xa000
	global_load_lds_dwordx4 v[4:5], off
	v_lshl_add_u64 v[0:1], v[0:1], 0, s[12:13]
	s_mov_b32 m0, s62
	s_add_u32 s26, s52, 0x20080
	global_load_lds_dwordx4 v[0:1], off
	v_lshl_add_u64 v[0:1], v[2:3], 0, s[12:13]
	s_mov_b32 m0, s63
	s_addc_u32 s27, s53, 0
	global_load_lds_dwordx4 v[0:1], off
	s_add_i32 m0, s49, 0x1c000
	v_lshl_add_u64 v[0:1], s[26:27], 0, v[130:131]
	global_load_lds_dwordx4 v[0:1], off
	v_lshl_add_u64 v[0:1], s[26:27], 0, v[134:135]
	s_add_i32 m0, s49, 0x1e000
	v_and_b32_e32 v2, 15, v8
	global_load_lds_dwordx4 v[0:1], off
	v_and_b32_e32 v3, 48, v8
	v_lshlrev_b32_e32 v1, 2, v2
	v_lshl_or_b32 v0, v2, 6, v3
	v_and_b32_e32 v4, 32, v1
	s_cmpk_lt_u32 s36, 0x100
	s_sext_i32_i16 s67, s8
	v_bitop3_b32 v5, v0, s37, v4 bitop3:0xde
	s_cselect_b64 s[36:37], -1, 0
	s_lshl_b32 s8, s33, 2
	s_or_b32 s8, s8, s9
	s_mul_i32 s26, s8, 0x900
	s_lshl_b32 s8, s33, 8
	s_add_i32 s8, s8, 0
	s_add_i32 s8, s8, 0x24800
	v_add_u32_e32 v149, s8, v1
	s_lshl_b32 s8, s9, 7
	s_add_u32 s8, s34, s8
	v_bitop3_b32 v146, v0, s38, v4 bitop3:0xde
	v_and_b32_e32 v0, 0x70, v12
	s_addc_u32 s9, s35, 0
	v_mov_b32_e32 v1, v131
	v_lshl_add_u64 v[136:137], s[8:9], 0, v[0:1]
	s_add_i32 s8, s26, 0
	s_add_i32 s8, s8, 0x20000
	s_movk_i32 s27, 0x90
	v_mov_b32_e32 v1, s8
	v_mad_u32_u24 v1, v2, s27, v1
	v_lshlrev_b32_e32 v2, 15, v9
	v_and_b32_e32 v2, 0xffff0000, v2
	v_lshl_add_u32 v2, v10, 12, v2
	v_and_b32_e32 v6, 1, v9
	v_lshl_or_b32 v2, v6, 6, v2
	v_lshl_add_u32 v138, v11, 1, v2
	v_lshlrev_b32_e32 v2, 15, v13
	v_and_b32_e32 v2, 0xffff0000, v2
	s_waitcnt vmcnt(6)
	v_bfe_u32 v147, v8, 3, 3
	v_lshl_add_u32 v2, v14, 12, v2
	v_and_b32_e32 v6, 1, v13
	v_mul_u32_u24_e32 v4, 0x90, v147
	v_add_u32_e32 v0, s8, v0
	v_lshl_or_b32 v2, v6, 6, v2
	s_add_i32 s64, 0, 0x10000
	s_add_i32 s65, 0, 0x14000
	v_or_b32_e32 v148, 8, v147
	v_mov_b32_e32 v139, v131
	v_lshl_add_u32 v140, v15, 1, v2
	v_mov_b32_e32 v141, v131
	v_mov_b64_e32 v[142:143], 0x1000
	v_mov_b64_e32 v[144:145], 0xfff
	v_add_u32_e32 v150, s64, v146
	v_add_u32_e32 v151, s65, v146
	v_add_u32_e32 v152, 0, v5
	v_add_u32_e32 v153, v1, v3
	v_add_u32_e32 v154, v0, v4
	s_movk_i32 s66, 0x4080
	s_barrier
	s_waitcnt vmcnt(0)
	s_cmpk_gt_u32 s81, 0xff
	s_cbranch_scc0 .Lsp_6
	s_setprio 1
.Lsp_6:
	s_branch .LBB0_862
.LBB0_860:
	s_mov_b64 s[8:9], 0

; #define PG8_LAS __attribute__((address_space(3)))
; #define PG8_STAGE(bufoff, gbase, voff) do { _Pragma("unroll") for (int _i = 0; _i < 2; ++_i) \
;         __builtin_amdgcn_global_load_lds((const unsigned*)((const char*)(gbase) + (voff)[_i]), (PG8_LAS unsigned*)(lds + (bufoff) + ldsw + _i * 8192), 16, 0, 0); } while (0)
; #define PG8_WAIT_V(n) asm volatile("s_waitcnt vmcnt(" #n ")" ::: "memory")
; #define PG8_BAR __builtin_amdgcn_s_barrier()
; template <class Epi, class Sched, bool ALIGN_EPI = false, bool SP2 = false>
; __device__ __forceinline__ void gemm_phase(PG8_LAS unsigned char* lds, const Gemm g, const Sched& S, const Epi& E, int tid_in) {
;     ...
;         PG8_WAIT_V(2); PG8_BAR;
;         PG8_STAGE(PG8_SB(1, 0), cB + kstep, voffB); PG8_STAGE(PG8_SA(1, 0), cA + kstep, voffA); PG8_STAGE(PG8_SB(1, 1), cB + hstepB + kstep, voffB);
;         PG8_WAIT_V(6); PG8_BAR;
;     __device__ __forceinline__ void operator()(const f32x4 (&acc)[2][2][4][2], const Unit& u, int wr, int wc, int fr, int fq) const {
;         const int lane = fr + 16 * fq, r = lane >> 2, p = lane & 3; PG8_LAS unsigned char* stg = lds + STG_OFF + (wr * 4 + wc) * STG_WAVE;
; #pragma unroll
;         for (int ai = 0; ai < 2; ++ai)
; #pragma unroll
;             for (int m = 0; m < 4; ++m) {
;                 const int row = u.pm * BM + ai * HALF + wr * 64 + m * 16 + r; float q = 0.f;
; #pragma unroll
;                 for (int bj = 0; bj < 2; ++bj) {
;                     const size_t off = (size_t)row * 2048 + u.pn * BM + wc * 64 + bj * 32 + 8 * p;
.LBB0_937:
	s_mov_b64 s[38:39], 0x80
	s_and_b32 s6, s6, 3
	s_add_i32 m0, s49, 0x18000
	v_lshl_add_u64 v[6:7], v[6:7], 0, s[38:39]
	s_lshl_b32 s9, s7, 13
	s_lshl_b32 s11, s6, 12
	s_waitcnt vmcnt(2)
	s_barrier
	global_load_lds_dwordx4 v[6:7], off
	v_lshl_add_u64 v[4:5], v[4:5], 0, s[38:39]
	s_add_i32 m0, s49, 0x1a000
	s_add_i32 s61, s49, 0x8000
	s_add_i32 s62, s49, 0xa000
	global_load_lds_dwordx4 v[4:5], off
	v_lshl_add_u64 v[0:1], v[0:1], 0, s[38:39]
	s_mov_b32 m0, s61
	s_add_u32 s26, s52, 0x80080
	global_load_lds_dwordx4 v[0:1], off
	v_lshl_add_u64 v[0:1], v[2:3], 0, s[38:39]
	s_mov_b32 m0, s62
	s_addc_u32 s27, s53, 0
	global_load_lds_dwordx4 v[0:1], off
	s_add_i32 m0, s49, 0x1c000
	v_lshl_add_u64 v[0:1], s[26:27], 0, v[130:131]
	global_load_lds_dwordx4 v[0:1], off
	v_lshl_add_u64 v[0:1], s[26:27], 0, v[134:135]
	s_add_i32 m0, s49, 0x1e000
	v_and_b32_e32 v2, 48, v8
	global_load_lds_dwordx4 v[0:1], off
	v_and_b32_e32 v0, 15, v8
	v_lshlrev_b32_e32 v3, 2, v8
	v_lshl_or_b32 v1, v0, 6, v2
	v_and_b32_e32 v3, 32, v3
	s_cmpk_lt_u32 s10, 0x100
	v_bitop3_b32 v4, v1, s9, v3 bitop3:0xde
	s_cselect_b64 s[40:41], -1, 0
	s_lshl_b32 s9, s7, 2
	s_or_b32 s9, s9, s6
	s_mulk_i32 s9, 0x900
	v_bitop3_b32 v137, v1, s11, v3 bitop3:0xde
	v_and_b32_e32 v3, 3, v8
	s_add_i32 s9, s9, 0
	v_bfe_u32 v1, v8, 2, 4
	v_lshlrev_b32_e32 v5, 3, v3
	s_add_i32 s9, s9, 0x20000
	v_lshl_or_b32 v150, s7, 6, v1
	v_lshl_or_b32 v136, s6, 6, v5
	v_lshlrev_b32_e32 v5, 5, v3
	v_cmp_eq_u32_e64 s[6:7], 0, v3
	s_movk_i32 s10, 0x90
	v_mov_b32_e32 v3, s9
	v_mad_u32_u24 v6, v0, s10, v3
	v_and_b32_e32 v0, 64, v252
	v_add_u32_e32 v0, 64, v0
	v_cmp_lt_i32_e32 vcc, v254, v0
	v_mad_u32_u24 v3, v1, s10, v3
	s_mov_b32 s9, 0x20400
	v_cndmask_b32_e32 v1, v252, v254, vcc
	v_cmp_lt_i32_e32 vcc, v253, v0
	v_lshlrev_b32_e32 v151, 2, v1
	v_lshrrev_b32_e32 v1, 1, v9
	v_cndmask_b32_e32 v0, v252, v253, vcc
	v_lshlrev_b32_e32 v152, 2, v0
	v_mul_lo_u32 v0, v11, s8
	v_mad_u64_u32 v[0:1], s[10:11], v1, s9, v[0:1]
	v_or_b32_e32 v0, v0, v10
	v_add_lshl_u32 v0, v0, v12, 1
	v_mov_b32_e32 v1, v131
	s_mov_b64 s[10:11], 0x204080
	v_lshl_add_u64 v[138:139], v[0:1], 0, s[10:11]
	v_lshrrev_b32_e32 v1, 1, v13
	v_mul_lo_u32 v0, v14, s8
	v_mad_u64_u32 v[0:1], s[8:9], v1, s9, v[0:1]
	s_waitcnt vmcnt(6)
	v_or_b32_e32 v0, v0, v15
	v_add_lshl_u32 v0, v0, v16, 1
	v_mov_b32_e32 v1, v131
	s_add_i32 s63, 0, 0x10000
	s_add_i32 s64, 0, 0x14000
	v_lshl_add_u64 v[140:141], v[0:1], 0, s[10:11]
	v_mov_b64_e32 v[142:143], 0x400
	v_mov_b64_e32 v[144:145], 0x3ff
	v_add_u32_e32 v153, s63, v137
	v_add_u32_e32 v154, s64, v137
	v_add_u32_e32 v155, 0, v4
	v_add_u32_e32 v156, v6, v2
	v_add_u32_e32 v157, v3, v5
	s_barrier
	s_cmpk_gt_u32 s81, 0xff
	s_cbranch_scc0 .Lsp_7
	s_setprio 1
.Lsp_7:
	s_branch .LBB0_940
.LBB0_938:
	s_mov_b64 s[8:9], 0
